# stack9: attention prefetches the next q-block unit's tile-0 K/V and Q rows before the current unit's output stores (full vmcnt drain at next unit start)
# baseline (speedup 1.0000x reference)
; #define LDS_WAIT() asm volatile("s_waitcnt lgkmcnt(0)" ::: "memory")
; DI float half_sum(float x) { const auto rr = __builtin_amdgcn_permlane32_swap(__float_as_uint(x), __float_as_uint(x), false, false); return __uint_as_float(rr[0]) + __uint_as_float(rr[1]); }
; DI void attn_unit(const bf16_t* Qb, const bf16_t* Kb, const bf16_t* Vt, bf16_t* MIX, int b, int h, int qb, char* lds, int tid_in) {
;     ...
;     { const bf16_t* qp = Qb + (rowbase + q0 + 32 * wave + r) * QW + h * 96 + 8 * hh;
; #pragma unroll
;         for (int ds = 0; ds < 6; ++ds) qr[ds] = *(const bf16x8*)(qp + 16 * ds); }
;     ...
;     l_run = half_sum(l_run);
;     if (hh == 0) wsf[r] = 1.f / l_run;
;     LDS_WAIT();
;     bf16_t* op = MIX + (rowbase + q0 + 32 * wave) * DM + h * 64;
.LBB0_443:
	s_mov_b32 s100, 0
	s_ashr_i32 s22, s4, 5
	s_ashr_i32 s23, s22, 31
	s_and_b32 s5, s4, 3
	s_bfe_u32 s2, s4, 0x30002
	s_lshl_b64 s[26:27], s[22:23], 12
	s_xor_b32 s12, s5, 15
	s_or_b32 s13, s5, 4
	s_xor_b32 s36, s5, 11
	v_lshl_add_u64 v[144:145], s[26:27], 0, v[142:143]
	s_mul_i32 s8, s2, 0xc0
	v_readlane_b32 s26, v240, 27
	v_readlane_b32 s27, v240, 28
	s_add_u32 s40, s26, s8
	s_addc_u32 s41, s27, 0
	s_mul_i32 s16, s22, 0x600000
	v_readlane_b32 s26, v241, 22
	s_mul_hi_i32 s9, s22, 0x600000
	v_readlane_b32 s27, v241, 23
	s_add_u32 s25, s26, s16
	s_addc_u32 s26, s27, s9
	s_lshl_b32 s22, s22, 3
	s_or_b32 s22, s22, s2
	s_ashr_i32 s23, s22, 31
	s_lshl_b64 s[22:23], s[22:23], 19
	v_readlane_b32 s38, v241, 24
	v_readlane_b32 s39, v241, 25
	s_add_u32 s42, s38, s22
	s_addc_u32 s43, s39, s23
	s_add_u32 s44, s25, s8
	s_addc_u32 s45, s26, 0
	s_lshl_b32 s2, s2, 7
	v_readlane_b32 s25, v240, 12
	s_add_u32 s46, s25, s2
	v_readlane_b32 s2, v240, 13
	s_addc_u32 s47, s2, 0
	s_or_b32 s2, s16, s8
	s_add_u32 s48, s2, 0x16a30000
	s_addc_u32 s49, s9, 0
	s_add_u32 s50, s22, 0x19a00100
	s_movk_i32 s25, 0x4000
	s_addc_u32 s51, s23, 0
	s_mov_b32 s37, 0
	s_branch .LBB0_445
.LBB0_444:
	s_or_b64 exec, exec, s[52:53]
	s_cmp_lt_u32 s37, 3
	s_cbranch_scc0 .Lattn_pf_skip
	s_cmp_eq_u32 s37, 0
	s_cselect_b32 s8, s5, s12
	s_cselect_b32 s9, s12, s13
	s_cmp_eq_u32 s37, 2
	s_cselect_b32 s8, s13, s8
	s_cselect_b32 s9, s36, s9
	s_sub_i32 s8, s9, s8
	s_mul_hi_i32 s9, s8, 0x60000
	s_mul_i32 s8, s8, 0x60000
	s_sub_u32 s22, s44, s48
	s_subb_u32 s23, s45, s49
	s_mul_i32 s16, s61, 0x30000
	s_sub_u32 s22, s22, s16
	s_subb_u32 s23, s23, 0
	s_sub_u32 s26, s42, s50
	s_subb_u32 s27, s43, s51
	s_lshl_b32 s16, s61, 8
	s_sub_u32 s26, s26, s16
	s_subb_u32 s27, s27, 0
	v_lshl_add_u64 v[250:251], v[152:153], 0, s[22:23]
	v_lshl_add_u64 v[252:253], v[154:155], 0, s[22:23]
	global_load_dwordx4 v[98:101], v[250:251], off
	global_load_dwordx4 v[102:105], v[252:253], off
	v_lshl_add_u64 v[250:251], v[156:157], 0, s[22:23]
	v_lshl_add_u64 v[252:253], v[158:159], 0, s[26:27]
	global_load_dwordx4 v[106:109], v[250:251], off
	global_load_dwordx4 v[110:113], v[252:253], off
	v_lshl_add_u64 v[250:251], v[160:161], 0, s[26:27]
	v_lshl_add_u64 v[252:253], v[254:255], 0, s[8:9]
	global_load_dwordx4 v[114:117], v[250:251], off
	global_load_dwordx4 v[118:121], v[252:253], off
	global_load_dwordx4 v[122:125], v[252:253], off offset:32
	global_load_dwordx4 v[126:129], v[252:253], off offset:64
	global_load_dwordx4 v[130:133], v[252:253], off offset:96
	global_load_dwordx4 v[134:137], v[252:253], off offset:128
	global_load_dwordx4 v[138:141], v[252:253], off offset:160
	s_mov_b32 s100, 1
; #define LDS_WAIT() asm volatile("s_waitcnt lgkmcnt(0)" ::: "memory")
; DI unsigned short f2bf(float f) { return (unsigned short)(pg8::cvt_pk_bf16(f, 0.f) & 0xffffu); }
; DI float half_sum(float x) { const auto rr = __builtin_amdgcn_permlane32_swap(__float_as_uint(x), __float_as_uint(x), false, false); return __uint_as_float(rr[0]) + __uint_as_float(rr[1]); }
; DI int crow(int r, int h) { return (r & 3) + 8 * (r >> 2) + 4 * h; }
; DI void attn_unit(const bf16_t* Qb, const bf16_t* Kb, const bf16_t* Vt, bf16_t* MIX, int b, int h, int qb, char* lds, int tid_in) {
;     ...
;     l_run = half_sum(l_run);
;     if (hh == 0) wsf[r] = 1.f / l_run;
;     LDS_WAIT();
;     bf16_t* op = MIX + (rowbase + q0 + 32 * wave) * DM + h * 64;
;     const int ob = 4 * hh * DM + r;
; #pragma unroll
;     for (int i = 0; i < 16; ++i) { const int q = crow(i, hh); const float f = wsf[q]; const int oi = ob + ((i & 3) + 8 * (i >> 2)) * DM; op[oi] = f2bf(o0[i] * f); op[oi + 32] = f2bf(o1[i] * f); }
;     __syncthreads();
.Lattn_pf_skip:
	s_waitcnt lgkmcnt(0)
	ds_read_b32 v0, v149
	v_lshlrev_b64 v[34:35], 11, v[146:147]
	v_lshl_or_b32 v36, v165, 12, v164
	v_lshl_add_u64 v[34:35], s[46:47], 0, v[34:35]
	v_ashrrev_i32_e32 v37, 31, v36
	s_waitcnt lgkmcnt(0)
	v_mul_f32_e32 v18, v18, v0
	v_lshl_add_u64 v[34:35], v[36:37], 1, v[34:35]
	v_mul_f32_e32 v0, v2, v0
	v_cvt_pk_bf16_f32 v18, v18, v1
	global_store_short v[34:35], v18, off
	v_cvt_pk_bf16_f32 v0, v0, v1
	ds_read_b32 v2, v149 offset:4
	global_store_short v[34:35], v0, off offset:64
	s_movk_i32 s2, 0x1000
	s_add_i32 s37, s37, 1
	s_cmp_eq_u32 s37, 4
	s_waitcnt lgkmcnt(0)
	v_mul_f32_e32 v0, v19, v2
	v_cvt_pk_bf16_f32 v0, v0, v1
	global_store_short v[34:35], v0, off offset:2048
	v_mul_f32_e32 v0, v3, v2
	v_cvt_pk_bf16_f32 v0, v0, v1
	ds_read_b32 v18, v149 offset:8
	global_store_short v[34:35], v0, off offset:2112
	v_add_co_u32_e32 v2, vcc, s2, v34
	s_movk_i32 s2, 0x5000
	s_waitcnt lgkmcnt(0)
	v_mul_f32_e32 v0, v20, v18
	v_cvt_pk_bf16_f32 v0, v0, v1
	v_addc_co_u32_e32 v3, vcc, 0, v35, vcc
	global_store_short v[2:3], v0, off
	v_mul_f32_e32 v0, v4, v18
	v_cvt_pk_bf16_f32 v0, v0, v1
	ds_read_b32 v4, v149 offset:12
	global_store_short v[2:3], v0, off offset:64
	s_waitcnt lgkmcnt(0)
	v_mul_f32_e32 v0, v21, v4
	v_cvt_pk_bf16_f32 v0, v0, v1
	global_store_short v[2:3], v0, off offset:2048
	v_mul_f32_e32 v0, v5, v4
	v_cvt_pk_bf16_f32 v0, v0, v1
	ds_read_b32 v4, v149 offset:32
	global_store_short v[2:3], v0, off offset:2112
	v_add_co_u32_e32 v2, vcc, s2, v34
	s_mov_b32 s2, 0x9000
	s_waitcnt lgkmcnt(0)
	v_mul_f32_e32 v0, v22, v4
	v_cvt_pk_bf16_f32 v0, v0, v1
	v_addc_co_u32_e32 v3, vcc, 0, v35, vcc
	global_store_short v[2:3], v0, off offset:-4096
	v_mul_f32_e32 v0, v6, v4
	v_cvt_pk_bf16_f32 v0, v0, v1
	ds_read_b32 v6, v149 offset:36
	v_add_co_u32_e32 v4, vcc, s25, v34
	s_nop 1
	v_addc_co_u32_e32 v5, vcc, 0, v35, vcc
	global_store_short v[4:5], v0, off offset:64
	s_waitcnt lgkmcnt(0)
	v_mul_f32_e32 v0, v23, v6
	v_cvt_pk_bf16_f32 v0, v0, v1
	global_store_short v[4:5], v0, off offset:2048
	v_mul_f32_e32 v0, v7, v6
	v_cvt_pk_bf16_f32 v0, v0, v1
	ds_read_b32 v6, v149 offset:40
	global_store_short v[4:5], v0, off offset:2112
	s_waitcnt lgkmcnt(0)
	v_mul_f32_e32 v0, v24, v6
	v_cvt_pk_bf16_f32 v0, v0, v1
	global_store_short v[2:3], v0, off
	v_mul_f32_e32 v0, v8, v6
	v_cvt_pk_bf16_f32 v0, v0, v1
	ds_read_b32 v4, v149 offset:44
	global_store_short v[2:3], v0, off offset:64
	s_waitcnt lgkmcnt(0)
	v_mul_f32_e32 v0, v25, v4
	v_cvt_pk_bf16_f32 v0, v0, v1
	global_store_short v[2:3], v0, off offset:2048
	v_mul_f32_e32 v0, v9, v4
	v_cvt_pk_bf16_f32 v0, v0, v1
	ds_read_b32 v4, v149 offset:64
	global_store_short v[2:3], v0, off offset:2112
	v_add_co_u32_e32 v2, vcc, s2, v34
	s_mov_b32 s2, 0x8000
	s_waitcnt lgkmcnt(0)
	v_mul_f32_e32 v0, v26, v4
	v_cvt_pk_bf16_f32 v0, v0, v1
	v_addc_co_u32_e32 v3, vcc, 0, v35, vcc
	global_store_short v[2:3], v0, off offset:-4096
	v_mul_f32_e32 v0, v10, v4
	v_cvt_pk_bf16_f32 v0, v0, v1
	ds_read_b32 v6, v149 offset:68
	v_add_co_u32_e32 v4, vcc, s2, v34
	s_mov_b32 s2, 0xd000
	s_nop 0
	v_addc_co_u32_e32 v5, vcc, 0, v35, vcc
	global_store_short v[4:5], v0, off offset:64
	s_waitcnt lgkmcnt(0)
	v_mul_f32_e32 v0, v27, v6
	v_cvt_pk_bf16_f32 v0, v0, v1
	global_store_short v[4:5], v0, off offset:2048
	v_mul_f32_e32 v0, v11, v6
	v_cvt_pk_bf16_f32 v0, v0, v1
	ds_read_b32 v6, v149 offset:72
	global_store_short v[4:5], v0, off offset:2112
	s_waitcnt lgkmcnt(0)
	v_mul_f32_e32 v0, v28, v6
	v_cvt_pk_bf16_f32 v0, v0, v1
	global_store_short v[2:3], v0, off
	v_mul_f32_e32 v0, v12, v6
	v_cvt_pk_bf16_f32 v0, v0, v1
	ds_read_b32 v4, v149 offset:76
	global_store_short v[2:3], v0, off offset:64
	s_waitcnt lgkmcnt(0)
	v_mul_f32_e32 v0, v29, v4
	v_cvt_pk_bf16_f32 v0, v0, v1
	global_store_short v[2:3], v0, off offset:2048
	v_mul_f32_e32 v0, v13, v4
	v_cvt_pk_bf16_f32 v0, v0, v1
	ds_read_b32 v4, v149 offset:96
	global_store_short v[2:3], v0, off offset:2112
	v_add_co_u32_e32 v2, vcc, s2, v34
	s_mov_b32 s2, 0xc000
	s_waitcnt lgkmcnt(0)
	v_mul_f32_e32 v0, v30, v4
	v_cvt_pk_bf16_f32 v0, v0, v1
	v_addc_co_u32_e32 v3, vcc, 0, v35, vcc
	global_store_short v[2:3], v0, off offset:-4096
	v_mul_f32_e32 v0, v14, v4
	v_cvt_pk_bf16_f32 v0, v0, v1
	ds_read_b32 v6, v149 offset:100
	v_add_co_u32_e32 v4, vcc, s2, v34
	s_nop 1
	v_addc_co_u32_e32 v5, vcc, 0, v35, vcc
	global_store_short v[4:5], v0, off offset:64
	s_waitcnt lgkmcnt(0)
	v_mul_f32_e32 v0, v31, v6
	v_cvt_pk_bf16_f32 v0, v0, v1
	global_store_short v[4:5], v0, off offset:2048
	v_mul_f32_e32 v0, v15, v6
	v_cvt_pk_bf16_f32 v0, v0, v1
	ds_read_b32 v6, v149 offset:104
	global_store_short v[4:5], v0, off offset:2112
	s_waitcnt lgkmcnt(0)
	v_mul_f32_e32 v0, v32, v6
	v_cvt_pk_bf16_f32 v0, v0, v1
	global_store_short v[2:3], v0, off
	v_mul_f32_e32 v0, v16, v6
	v_cvt_pk_bf16_f32 v0, v0, v1
	ds_read_b32 v4, v149 offset:108
	global_store_short v[2:3], v0, off offset:64
	s_waitcnt lgkmcnt(0)
	v_mul_f32_e32 v0, v33, v4
	v_cvt_pk_bf16_f32 v0, v0, v1
	global_store_short v[2:3], v0, off offset:2048
	v_mul_f32_e32 v0, v17, v4
	v_cvt_pk_bf16_f32 v0, v0, v1
	global_store_short v[2:3], v0, off offset:2112
	s_barrier
	s_cbranch_scc1 .LBB0_442

; DI int opaque_lane() { int l; asm volatile("v_mbcnt_lo_u32_b32 %0, -1, 0\n\tv_mbcnt_hi_u32_b32 %0, -1, %0" : "=v"(l)); return l; }
; DI void attn_unit(const bf16_t* Qb, const bf16_t* Kb, const bf16_t* Vt, bf16_t* MIX, int b, int h, int qb, char* lds, int tid_in) {
;     const int lane = opaque_lane(), wave = tid_in >> 6, tid = wave * 64 + lane, r = lane & 31, hh = lane >> 5;
;     const size_t rowbase = (size_t)b * SEQ; const int q0 = qb * 256;
;     bf16x8 qr[6];
;     { const bf16_t* qp = Qb + (rowbase + q0 + 32 * wave + r) * QW + h * 96 + 8 * hh;
; #pragma unroll
;         for (int ds = 0; ds < 6; ++ds) qr[ds] = *(const bf16x8*)(qp + 16 * ds); }
;     f32x16 o0 = {}, o1 = {};
;     float m_run = 0.f, l_run = 0.f;
;     const int NT = 2 * (qb + 1);
;     const bf16_t* Kh = Kb + rowbase * QW + h * 96; const bf16_t* Vh = Vt + (size_t)(b * 8 + h) * 64 * SEQ;
;     float* wsf = (float*)(lds + A_SC) + wave * 32;
;     const int qabs = q0 + 32 * wave + r;
;     u32x4 kreg[3], vreg[2];
;     int kgo[3], klo[3], vgo[2], vlo[2];
; #pragma unroll
;     for (int i = 0; i < 3; ++i) { const int q = tid + 512 * i, kv = q / 12, ck = q % 12; kgo[i] = kv * QW + ck * 8; klo[i] = ck * 2048 + kv * 16; }
; #pragma unroll
;     for (int i = 0; i < 2; ++i) { const int q = tid + 512 * i, d = q >> 4, pc = q & 15; vgo[i] = d * SEQ + pc * 8; vlo[i] = AK_BYTES + d * AV_PITCH + (16 * (pc >> 1) + 4 * (pc & 1)) * 2; }
;     auto gload = [&](int t) {
;         const bf16_t* kt = Kh + (size_t)t * 128 * QW; const bf16_t* vt = Vh + t * 128;
; #pragma unroll
;         for (int i = 0; i < 3; ++i) kreg[i] = *(const u32x4*)(kt + kgo[i]);
; #pragma unroll
;         for (int i = 0; i < 2; ++i) vreg[i] = *(const u32x4*)(vt + vgo[i]);
;     };
;     auto lstore = [&](int buf) {
;         char* bb_ = lds + buf * ABUF;
; #pragma unroll
;         for (int i = 0; i < 3; ++i) *(u32x4*)(bb_ + klo[i]) = kreg[i];
; #pragma unroll
;         for (int i = 0; i < 2; ++i) { u32x2 lo; lo.x = vreg[i].x; lo.y = vreg[i].y; u32x2 hi; hi.x = vreg[i].z; hi.y = vreg[i].w;
;             *(u32x2*)(bb_ + vlo[i]) = lo; *(u32x2*)(bb_ + vlo[i] + 16) = hi; }
;     };
;     gload(0); lstore(0); __syncthreads();
; #pragma unroll
;     for (int ds = 0; ds < 6; ++ds) asm volatile("" : "+v"(qr[ds]));
.LBB0_450:
	s_cmp_lg_u32 s100, 0
	s_cbranch_scc1 .Lattn_pf_start
	s_lshl_b32 s62, s2, 8
	v_mbcnt_lo_u32_b32 v16, -1, 0
	v_mbcnt_hi_u32_b32 v16, -1, v16
	v_lshl_add_u64 v[146:147], v[144:145], 0, s[62:63]
	v_and_b32_e32 v164, 31, v16
	v_or_b32_e32 v0, v146, v164
	v_mov_b64_e32 v[2:3], s[40:41]
	v_mad_u64_u32 v[2:3], s[22:23], v0, s14, v[2:3]
	v_add_u32_e32 v0, v16, v162
	v_mul_hi_i32 v4, v0, s6
	v_lshrrev_b32_e32 v5, 31, v4
	v_ashrrev_i32_e32 v4, 1, v4
	v_add_u32_e32 v17, v4, v5
	v_add_u32_e32 v5, 0x200, v0
	v_mul_hi_i32 v6, v5, s6
	v_lshrrev_b32_e32 v7, 31, v6
	v_ashrrev_i32_e32 v6, 1, v6
	v_add_u32_e32 v19, v6, v7
	v_add_u32_e32 v7, 0x400, v0
	v_mul_hi_i32 v8, v7, s6
	v_lshrrev_b32_e32 v9, 31, v8
	v_ashrrev_i32_e32 v8, 1, v8
	v_mul_lo_u32 v4, v17, 12
	v_add_u32_e32 v21, v8, v9
	v_sub_u32_e32 v18, v0, v4
	v_mul_lo_u32 v4, v17, s18
	v_mul_lo_u32 v6, v19, 12
	v_mul_lo_u32 v8, v21, 12
	v_lshl_add_u32 v4, v18, 3, v4
	v_sub_u32_e32 v20, v5, v6
	v_mul_lo_u32 v6, v19, s18
	v_sub_u32_e32 v22, v7, v8
	v_mul_lo_u32 v7, v21, s18
	v_lshlrev_b32_e32 v23, 3, v16
	v_lshl_add_u32 v6, v20, 3, v6
	v_lshl_add_u32 v8, v22, 3, v7
	v_and_b32_e32 v24, 0x78, v23
	v_ashrrev_i32_e32 v25, 4, v0
	v_ashrrev_i32_e32 v26, 4, v5
	v_ashrrev_i32_e32 v5, 31, v4
	v_lshl_or_b32 v10, v25, 12, v24
	v_lshlrev_b64 v[4:5], 1, v[4:5]
	v_ashrrev_i32_e32 v7, 31, v6
	v_ashrrev_i32_e32 v9, 31, v8
	v_lshl_add_u64 v[12:13], s[44:45], 0, v[4:5]
	v_lshlrev_b64 v[6:7], 1, v[6:7]
	v_lshlrev_b64 v[8:9], 1, v[8:9]
	v_ashrrev_i32_e32 v11, 31, v10
	v_lshl_add_u64 v[14:15], s[44:45], 0, v[6:7]
	global_load_dwordx4 v[98:101], v[12:13], off
	global_load_dwordx4 v[102:105], v[14:15], off
	v_lshl_add_u64 v[12:13], s[44:45], 0, v[8:9]
	v_lshlrev_b64 v[10:11], 1, v[10:11]
	global_load_dwordx4 v[106:109], v[12:13], off
	v_lshl_add_u64 v[12:13], s[42:43], 0, v[10:11]
	global_load_dwordx4 v[110:113], v[12:13], off
	v_lshl_or_b32 v12, v26, 12, v24
	v_ashrrev_i32_e32 v13, 31, v12
	v_lshlrev_b64 v[12:13], 1, v[12:13]
	v_ashrrev_i32_e32 v165, 5, v16
	v_lshl_add_u64 v[14:15], s[42:43], 0, v[12:13]
	global_load_dwordx4 v[114:117], v[14:15], off
	v_lshlrev_b32_e32 v14, 3, v165
	v_mad_i32_i24 v3, v147, s14, v3
	v_ashrrev_i32_e32 v15, 31, v14
	v_lshl_add_u64 v[2:3], v[14:15], 1, v[2:3]
	v_mov_b64_e32 v[254:255], v[2:3]
	global_load_dwordx4 v[118:121], v[2:3], off
	global_load_dwordx4 v[122:125], v[2:3], off offset:32
	global_load_dwordx4 v[126:129], v[2:3], off offset:64
	global_load_dwordx4 v[130:133], v[2:3], off offset:96
	global_load_dwordx4 v[134:137], v[2:3], off offset:128
	global_load_dwordx4 v[138:141], v[2:3], off offset:160
	v_lshlrev_b32_e32 v0, 4, v16
	v_and_b32_e32 v0, 0xe0, v0
	v_lshlrev_b32_e32 v2, 4, v17
	v_and_or_b32 v0, v23, 8, v0
	v_lshlrev_b32_e32 v3, 4, v19
	v_lshlrev_b32_e32 v14, 4, v21
	v_lshl_add_u32 v167, v18, 11, v2
	v_mad_u64_u32 v[148:149], s[22:23], v25, s21, v[0:1]
	v_lshl_add_u32 v168, v20, 11, v3
	v_lshl_add_u32 v169, v22, 11, v14
	v_and_b32_e32 v249, 7, v18
	v_lshlrev_b32_e32 v249, 4, v249
	v_xor_b32_e32 v167, v167, v249
	v_and_b32_e32 v249, 7, v20
	v_lshlrev_b32_e32 v249, 4, v249
	v_xor_b32_e32 v168, v168, v249
	v_and_b32_e32 v249, 7, v22
	v_lshlrev_b32_e32 v249, 4, v249
	v_xor_b32_e32 v169, v169, v249
	v_add_u32_e32 v2, 0, v167
	v_mad_u64_u32 v[150:151], s[22:23], v26, s21, v[0:1]
	v_add_u32_e32 v3, 0, v168
	v_add_u32_e32 v14, 0, v169
	v_add_u32_e32 v0, 0, v150
	v_add_u32_e32 v0, 0x6000, v0
	v_mov_b32_e32 v15, v1
	v_lshl_add_u64 v[152:153], s[48:49], 0, v[4:5]
	v_lshl_add_u64 v[154:155], s[48:49], 0, v[6:7]
	v_lshl_add_u64 v[156:157], s[48:49], 0, v[8:9]
	v_lshl_add_u64 v[158:159], s[50:51], 0, v[10:11]
	v_lshl_add_u64 v[160:161], s[50:51], 0, v[12:13]
	v_mov_b32_e32 v4, v1
	v_mov_b32_e32 v5, v1
	v_mov_b32_e32 v6, v1
	v_mov_b32_e32 v7, v1
	v_mov_b32_e32 v8, v1
	v_mov_b32_e32 v9, v1
	v_mov_b32_e32 v10, v1
	s_waitcnt vmcnt(10)
	ds_write_b128 v2, v[98:101]
	s_waitcnt vmcnt(9)
	ds_write_b128 v3, v[102:105]
	s_waitcnt vmcnt(8)
	ds_write_b128 v14, v[106:109]
	v_add_u32_e32 v2, 0, v148
	v_add_u32_e32 v2, 0x6000, v2
	v_mov_b32_e32 v14, v1
	s_waitcnt vmcnt(7)
	ds_write2_b64 v2, v[110:111], v[112:113] offset1:2
	v_mov_b32_e32 v2, v1
	v_mov_b32_e32 v3, v1
	v_mov_b32_e32 v11, v1
	v_mov_b32_e32 v12, v1
	v_mov_b32_e32 v13, v1
	s_waitcnt vmcnt(6)
	ds_write2_b64 v0, v[114:115], v[116:117] offset1:2
	v_mov_b32_e32 v0, v1
	v_mov_b64_e32 v[32:33], v[14:15]
	s_lshl_b32 s61, s2, 1
	v_add_u32_e32 v166, s62, v142
	v_cmp_gt_u32_e64 s[38:39], 32, v16
	v_lshlrev_b32_e32 v176, 4, v165
	v_mov_b64_e32 v[30:31], v[12:13]
	v_mov_b64_e32 v[28:29], v[10:11]
	v_mov_b64_e32 v[26:27], v[8:9]
	v_mov_b64_e32 v[24:25], v[6:7]
	v_mov_b64_e32 v[22:23], v[4:5]
	v_mov_b64_e32 v[20:21], v[2:3]
	v_mov_b64_e32 v[18:19], v[0:1]
	v_mov_b64_e32 v[16:17], v[14:15]
	s_mov_b32 s60, 1
	s_add_i32 s61, s61, 2
	v_or_b32_e32 v170, v164, v166
	v_or_b32_e32 v171, 31, v166
	v_lshlrev_b32_e32 v172, 11, v165
	v_lshlrev_b32_e32 v173, 4, v164
	v_lshlrev_b32_e32 v249, 4, v165
	v_xor_b32_e32 v173, v173, v249
	v_lshlrev_b32_e32 v174, 2, v165
	v_lshl_add_u32 v151, v164, 2, v163
	v_mul_u32_u24_e32 v175, 0x110, v164
	v_add_u32_e32 v149, v163, v176
	s_addk_i32 s62, 0x100
	s_mov_b32 s74, 0
	v_mov_b32_e32 v177, 0
	v_mov_b64_e32 v[14:15], v[12:13]
	v_mov_b64_e32 v[12:13], v[10:11]
	v_mov_b64_e32 v[10:11], v[8:9]
	v_mov_b64_e32 v[8:9], v[6:7]
	v_mov_b64_e32 v[6:7], v[4:5]
	v_mov_b64_e32 v[4:5], v[2:3]
	v_mov_b64_e32 v[2:3], v[0:1]
	v_mov_b32_e32 v0, 0
	s_waitcnt lgkmcnt(0)
	s_barrier
	s_waitcnt vmcnt(5)
	s_waitcnt vmcnt(4)
	s_waitcnt vmcnt(3)
	s_waitcnt vmcnt(2)
	s_waitcnt vmcnt(1)
	s_waitcnt vmcnt(0)
	s_branch .LBB0_452
; DI int opaque_lane() { int l; asm volatile("v_mbcnt_lo_u32_b32 %0, -1, 0\n\tv_mbcnt_hi_u32_b32 %0, -1, %0" : "=v"(l)); return l; }
; DI void attn_unit(const bf16_t* Qb, const bf16_t* Kb, const bf16_t* Vt, bf16_t* MIX, int b, int h, int qb, char* lds, int tid_in) {
;     const int lane = opaque_lane(), wave = tid_in >> 6, tid = wave * 64 + lane, r = lane & 31, hh = lane >> 5;
;     const size_t rowbase = (size_t)b * SEQ; const int q0 = qb * 256;
;     bf16x8 qr[6];
;     { const bf16_t* qp = Qb + (rowbase + q0 + 32 * wave + r) * QW + h * 96 + 8 * hh;
; #pragma unroll
;         for (int ds = 0; ds < 6; ++ds) qr[ds] = *(const bf16x8*)(qp + 16 * ds); }
;     f32x16 o0 = {}, o1 = {};
;     float m_run = 0.f, l_run = 0.f;
;     const int NT = 2 * (qb + 1);
;     const bf16_t* Kh = Kb + rowbase * QW + h * 96; const bf16_t* Vh = Vt + (size_t)(b * 8 + h) * 64 * SEQ;
;     float* wsf = (float*)(lds + A_SC) + wave * 32;
;     const int qabs = q0 + 32 * wave + r;
;     u32x4 kreg[3], vreg[2];
;     int kgo[3], klo[3], vgo[2], vlo[2];
; #pragma unroll
;     for (int i = 0; i < 3; ++i) { const int q = tid + 512 * i, kv = q / 12, ck = q % 12; kgo[i] = kv * QW + ck * 8; klo[i] = ck * 2048 + kv * 16; }
; #pragma unroll
;     for (int i = 0; i < 2; ++i) { const int q = tid + 512 * i, d = q >> 4, pc = q & 15; vgo[i] = d * SEQ + pc * 8; vlo[i] = AK_BYTES + d * AV_PITCH + (16 * (pc >> 1) + 4 * (pc & 1)) * 2; }
;     auto gload = [&](int t) {
;         const bf16_t* kt = Kh + (size_t)t * 128 * QW; const bf16_t* vt = Vh + t * 128;
; #pragma unroll
;         for (int i = 0; i < 3; ++i) kreg[i] = *(const u32x4*)(kt + kgo[i]);
; #pragma unroll
;         for (int i = 0; i < 2; ++i) vreg[i] = *(const u32x4*)(vt + vgo[i]);
;     };
;     auto lstore = [&](int buf) {
;         char* bb_ = lds + buf * ABUF;
; #pragma unroll
;         for (int i = 0; i < 3; ++i) *(u32x4*)(bb_ + klo[i]) = kreg[i];
; #pragma unroll
;         for (int i = 0; i < 2; ++i) { u32x2 lo; lo.x = vreg[i].x; lo.y = vreg[i].y; u32x2 hi; hi.x = vreg[i].z; hi.y = vreg[i].w;
;             *(u32x2*)(bb_ + vlo[i]) = lo; *(u32x2*)(bb_ + vlo[i] + 16) = hi; }
;     };
;     gload(0); lstore(0); __syncthreads();
; #pragma unroll
;     for (int ds = 0; ds < 6; ++ds) asm volatile("" : "+v"(qr[ds]));
.Lattn_pf_start:
	s_mov_b32 s100, 0
	s_lshl_b32 s62, s2, 8
	v_mbcnt_lo_u32_b32 v16, -1, 0
	v_mbcnt_hi_u32_b32 v16, -1, v16
	v_lshl_add_u64 v[146:147], v[144:145], 0, s[62:63]
	v_and_b32_e32 v164, 31, v16
	v_or_b32_e32 v0, v146, v164
	v_mov_b64_e32 v[2:3], s[40:41]
	v_mad_u64_u32 v[2:3], s[22:23], v0, s14, v[2:3]
	v_add_u32_e32 v0, v16, v162
	v_mul_hi_i32 v4, v0, s6
	v_lshrrev_b32_e32 v5, 31, v4
	v_ashrrev_i32_e32 v4, 1, v4
	v_add_u32_e32 v17, v4, v5
	v_add_u32_e32 v5, 0x200, v0
	v_mul_hi_i32 v6, v5, s6
	v_lshrrev_b32_e32 v7, 31, v6
	v_ashrrev_i32_e32 v6, 1, v6
	v_add_u32_e32 v19, v6, v7
	v_add_u32_e32 v7, 0x400, v0
	v_mul_hi_i32 v8, v7, s6
	v_lshrrev_b32_e32 v9, 31, v8
	v_ashrrev_i32_e32 v8, 1, v8
	v_mul_lo_u32 v4, v17, 12
	v_add_u32_e32 v21, v8, v9
	v_sub_u32_e32 v18, v0, v4
	v_mul_lo_u32 v4, v17, s18
	v_mul_lo_u32 v6, v19, 12
	v_mul_lo_u32 v8, v21, 12
	v_lshl_add_u32 v4, v18, 3, v4
	v_sub_u32_e32 v20, v5, v6
	v_mul_lo_u32 v6, v19, s18
	v_sub_u32_e32 v22, v7, v8
	v_mul_lo_u32 v7, v21, s18
	v_lshlrev_b32_e32 v23, 3, v16
	v_lshl_add_u32 v6, v20, 3, v6
	v_lshl_add_u32 v8, v22, 3, v7
	v_and_b32_e32 v24, 0x78, v23
	v_ashrrev_i32_e32 v25, 4, v0
	v_ashrrev_i32_e32 v26, 4, v5
	v_ashrrev_i32_e32 v5, 31, v4
	v_lshl_or_b32 v10, v25, 12, v24
	v_lshlrev_b64 v[4:5], 1, v[4:5]
	v_ashrrev_i32_e32 v7, 31, v6
	v_ashrrev_i32_e32 v9, 31, v8
	v_lshl_add_u64 v[12:13], s[44:45], 0, v[4:5]
	v_lshlrev_b64 v[6:7], 1, v[6:7]
	v_lshlrev_b64 v[8:9], 1, v[8:9]
	v_ashrrev_i32_e32 v11, 31, v10
	v_lshl_add_u64 v[14:15], s[44:45], 0, v[6:7]
	v_lshl_add_u64 v[12:13], s[44:45], 0, v[8:9]
	v_lshlrev_b64 v[10:11], 1, v[10:11]
	v_lshl_add_u64 v[12:13], s[42:43], 0, v[10:11]
	v_lshl_or_b32 v12, v26, 12, v24
	v_ashrrev_i32_e32 v13, 31, v12
	v_lshlrev_b64 v[12:13], 1, v[12:13]
	v_ashrrev_i32_e32 v165, 5, v16
	v_lshl_add_u64 v[14:15], s[42:43], 0, v[12:13]
	v_lshlrev_b32_e32 v14, 3, v165
	v_mad_i32_i24 v3, v147, s14, v3
	v_ashrrev_i32_e32 v15, 31, v14
	v_lshl_add_u64 v[2:3], v[14:15], 1, v[2:3]
	v_mov_b64_e32 v[254:255], v[2:3]
	v_lshlrev_b32_e32 v0, 4, v16
	v_and_b32_e32 v0, 0xe0, v0
	v_lshlrev_b32_e32 v2, 4, v17
	v_and_or_b32 v0, v23, 8, v0
	v_lshlrev_b32_e32 v3, 4, v19
	v_lshlrev_b32_e32 v14, 4, v21
	v_lshl_add_u32 v167, v18, 11, v2
	v_mad_u64_u32 v[148:149], s[22:23], v25, s21, v[0:1]
	v_lshl_add_u32 v168, v20, 11, v3
	v_lshl_add_u32 v169, v22, 11, v14
	v_and_b32_e32 v249, 7, v18
	v_lshlrev_b32_e32 v249, 4, v249
	v_xor_b32_e32 v167, v167, v249
	v_and_b32_e32 v249, 7, v20
	v_lshlrev_b32_e32 v249, 4, v249
	v_xor_b32_e32 v168, v168, v249
	v_and_b32_e32 v249, 7, v22
	v_lshlrev_b32_e32 v249, 4, v249
	v_xor_b32_e32 v169, v169, v249
	v_add_u32_e32 v2, 0, v167
	v_mad_u64_u32 v[150:151], s[22:23], v26, s21, v[0:1]
	v_add_u32_e32 v3, 0, v168
	v_add_u32_e32 v14, 0, v169
	v_add_u32_e32 v0, 0, v150
	v_add_u32_e32 v0, 0x6000, v0
	v_mov_b32_e32 v15, v1
	v_lshl_add_u64 v[152:153], s[48:49], 0, v[4:5]
	v_lshl_add_u64 v[154:155], s[48:49], 0, v[6:7]
	v_lshl_add_u64 v[156:157], s[48:49], 0, v[8:9]
	v_lshl_add_u64 v[158:159], s[50:51], 0, v[10:11]
	v_lshl_add_u64 v[160:161], s[50:51], 0, v[12:13]
	v_mov_b32_e32 v4, v1
	v_mov_b32_e32 v5, v1
	v_mov_b32_e32 v6, v1
	v_mov_b32_e32 v7, v1
	v_mov_b32_e32 v8, v1
	v_mov_b32_e32 v9, v1
	v_mov_b32_e32 v10, v1
	s_waitcnt vmcnt(0)
	ds_write_b128 v2, v[98:101]
	ds_write_b128 v3, v[102:105]
	ds_write_b128 v14, v[106:109]
	v_add_u32_e32 v2, 0, v148
	v_add_u32_e32 v2, 0x6000, v2
	v_mov_b32_e32 v14, v1
	ds_write2_b64 v2, v[110:111], v[112:113] offset1:2
	v_mov_b32_e32 v2, v1
	v_mov_b32_e32 v3, v1
	v_mov_b32_e32 v11, v1
	v_mov_b32_e32 v12, v1
	v_mov_b32_e32 v13, v1
	ds_write2_b64 v0, v[114:115], v[116:117] offset1:2
	v_mov_b32_e32 v0, v1
	v_mov_b64_e32 v[32:33], v[14:15]
	s_lshl_b32 s61, s2, 1
	v_add_u32_e32 v166, s62, v142
	v_cmp_gt_u32_e64 s[38:39], 32, v16
	v_lshlrev_b32_e32 v176, 4, v165
	v_mov_b64_e32 v[30:31], v[12:13]
	v_mov_b64_e32 v[28:29], v[10:11]
	v_mov_b64_e32 v[26:27], v[8:9]
	v_mov_b64_e32 v[24:25], v[6:7]
	v_mov_b64_e32 v[22:23], v[4:5]
	v_mov_b64_e32 v[20:21], v[2:3]
	v_mov_b64_e32 v[18:19], v[0:1]
	v_mov_b64_e32 v[16:17], v[14:15]
	s_mov_b32 s60, 1
	s_add_i32 s61, s61, 2
	v_or_b32_e32 v170, v164, v166
	v_or_b32_e32 v171, 31, v166
	v_lshlrev_b32_e32 v172, 11, v165
	v_lshlrev_b32_e32 v173, 4, v164
	v_lshlrev_b32_e32 v249, 4, v165
	v_xor_b32_e32 v173, v173, v249
	v_lshlrev_b32_e32 v174, 2, v165
	v_lshl_add_u32 v151, v164, 2, v163
	v_mul_u32_u24_e32 v175, 0x110, v164
	v_add_u32_e32 v149, v163, v176
	s_addk_i32 s62, 0x100
	s_mov_b32 s74, 0
	v_mov_b32_e32 v177, 0
	v_mov_b64_e32 v[14:15], v[12:13]
	v_mov_b64_e32 v[12:13], v[10:11]
	v_mov_b64_e32 v[10:11], v[8:9]
	v_mov_b64_e32 v[8:9], v[6:7]
	v_mov_b64_e32 v[6:7], v[4:5]
	v_mov_b64_e32 v[4:5], v[2:3]
	v_mov_b64_e32 v[2:3], v[0:1]
	v_mov_b32_e32 v0, 0
	s_waitcnt lgkmcnt(0)
	s_barrier
	s_branch .LBB0_452

; __global__ void __launch_bounds__(512, 2) hybrid_fwd(Params P) {
	.amdhsa_kernel _Z10hybrid_fwd6Params
		.amdhsa_group_segment_fixed_size 0
		.amdhsa_private_segment_fixed_size 0
		.amdhsa_kernarg_size 456
		.amdhsa_user_sgpr_count 2
		.amdhsa_user_sgpr_dispatch_ptr 0
		.amdhsa_user_sgpr_queue_ptr 0
		.amdhsa_user_sgpr_kernarg_segment_ptr 1
		.amdhsa_user_sgpr_dispatch_id 0
		.amdhsa_user_sgpr_kernarg_preload_length 0
		.amdhsa_user_sgpr_kernarg_preload_offset 0
		.amdhsa_user_sgpr_private_segment_size 0
		.amdhsa_uses_dynamic_stack 0
		.amdhsa_enable_private_segment 0
		.amdhsa_system_sgpr_workgroup_id_x 1
		.amdhsa_system_sgpr_workgroup_id_y 0
		.amdhsa_system_sgpr_workgroup_id_z 0
		.amdhsa_system_sgpr_workgroup_info 0
		.amdhsa_system_vgpr_workitem_id 2
		.amdhsa_next_free_vgpr 256
		.amdhsa_next_free_sgpr 102
		.amdhsa_accum_offset 256
		.amdhsa_reserve_vcc 1
		.amdhsa_float_round_mode_32 0
		.amdhsa_float_round_mode_16_64 0
		.amdhsa_float_denorm_mode_32 3
		.amdhsa_float_denorm_mode_16_64 3
		.amdhsa_dx10_clamp 1
		.amdhsa_ieee_mode 1
		.amdhsa_fp16_overflow 0
		.amdhsa_tg_split 0
		.amdhsa_exception_fp_ieee_invalid_op 0
		.amdhsa_exception_fp_denorm_src 0
		.amdhsa_exception_fp_ieee_div_zero 0
		.amdhsa_exception_fp_ieee_overflow 0
		.amdhsa_exception_fp_ieee_underflow 0
		.amdhsa_exception_fp_ieee_inexact 0
		.amdhsa_exception_int_div_zero 0
	.end_amdhsa_kernel

; __global__ void __launch_bounds__(512, 2) hybrid_fwd(Params P) {
amdhsa.kernels:
  - .agpr_count:     0
    .args:
      - .offset:         0
        .size:           200
        .value_kind:     by_value
      - .offset:         200
        .size:           4
        .value_kind:     hidden_block_count_x
      - .offset:         204
        .size:           4
        .value_kind:     hidden_block_count_y
      - .offset:         208
        .size:           4
        .value_kind:     hidden_block_count_z
      - .offset:         212
        .size:           2
        .value_kind:     hidden_group_size_x
      - .offset:         214
        .size:           2
        .value_kind:     hidden_group_size_y
      - .offset:         216
        .size:           2
        .value_kind:     hidden_group_size_z
      - .offset:         218
        .size:           2
        .value_kind:     hidden_remainder_x
      - .offset:         220
        .size:           2
        .value_kind:     hidden_remainder_y
      - .offset:         222
        .size:           2
        .value_kind:     hidden_remainder_z
      - .offset:         240
        .size:           8
        .value_kind:     hidden_global_offset_x
      - .offset:         248
        .size:           8
        .value_kind:     hidden_global_offset_y
      - .offset:         256
        .size:           8
        .value_kind:     hidden_global_offset_z
      - .offset:         264
        .size:           2
        .value_kind:     hidden_grid_dims
      - .offset:         288
        .size:           8
        .value_kind:     hidden_multigrid_sync_arg
      - .offset:         320
        .size:           4
        .value_kind:     hidden_dynamic_lds_size
    .group_segment_fixed_size: 0
    .kernarg_segment_align: 8
    .kernarg_segment_size: 456
    .language:       OpenCL C
    .language_version:
      - 2
      - 0
    .max_flat_workgroup_size: 512
    .name:           _Z10hybrid_fwd6Params
    .private_segment_fixed_size: 0
    .sgpr_count:     108
    .sgpr_spill_count: 332
    .symbol:         _Z10hybrid_fwd6Params.kd
    .uniform_work_group_size: 1
    .uses_dynamic_stack: false
    .vgpr_count:     256
    .vgpr_spill_count: 0
    .wavefront_size: 64
